# tail rebalancing: merge/out main pass capped at 1024 units, 8 leftover sample-tile units run on CUs 0-7 (merge, overlapped with out main) and CUs 8-15 (out); gbar3 split into arrive/wait plus a second
# speedup vs baseline: 1.0895x; 1.0092x over previous
; __global__ void __launch_bounds__(512, 2) mega_kernel(Params p) {
;   extern __shared__ __attribute__((aligned(16))) char smem[];
;   cg::grid_group grid = cg::this_grid();
;   phase_prologue(p, smem);
;   grid.sync();
;   unsigned* bar = reinterpret_cast<unsigned*>((reinterpret_cast<int*>(p.ws + OFF_CTR)) + 8);
;   unsigned nb = 0; const unsigned G = gridDim.x;
; #pragma nounroll
;   for (int l = 0; l < DEPTH; ++l) {
;     phase_proj(p, l, smem);
;     gbar(bar, ++nb * G);
;     phase_attn(p, l, smem);
;     gbar(bar, ++nb * G);
;     phase_merge(p, smem);
;     gbar(bar, ++nb * G);
;     phase_out(p, smem);
;     gbar(bar, ++nb * G);
;     phase_ln(p, l, smem);
;     if (l + 1 < DEPTH) gbar(bar, ++nb * G);
;   }
.LBB0_99:
	s_or_b64 exec, exec, s[0:1]
	v_readlane_b32 s0, v249, 0
	v_readlane_b32 s1, v249, 1
	s_add_u32 s2, s0, 0x38335020
	s_addc_u32 s3, s1, 0
	v_writelane_b32 v249, s2, 44
	v_mov_b32_e32 v17, 0
	v_mov_b32_e32 v182, 1
	v_writelane_b32 v249, s3, 45
	s_add_u32 s2, s0, 0x373b4000
	v_writelane_b32 v249, s2, 46
	s_addc_u32 s2, s1, 0
	v_writelane_b32 v249, s2, 47
	v_mov_b32_e32 v183, 0x10001
	v_readlane_b32 s4, v249, 2
	v_readlane_b32 s6, v249, 4
	v_readlane_b32 s7, v249, 5
	s_add_u32 s2, s6, 0x5cb00000
	s_addc_u32 s3, s7, 0
	v_readlane_b32 s5, v249, 3
	v_writelane_b32 v249, s2, 48
	v_mov_b32_e32 v152, 0x3727c5ac
	v_mov_b32_e32 v184, 0x40e
	v_writelane_b32 v249, s3, 49
	s_add_u32 s2, s0, 0x26ea0000
	s_addc_u32 s3, s1, 0
	v_writelane_b32 v249, s2, 50
	v_mov_b32_e32 v185, 0x41b17218
	v_mov_b32_e32 v20, 0x3f803f80
	v_writelane_b32 v249, s3, 51
	s_add_u32 s2, s6, 0x5ca80000
	s_addc_u32 s3, s7, 0
	v_writelane_b32 v249, s2, 52
	v_mov_b32_e32 v248, 0x22000
	v_mov_b64_e32 v[158:159], 0x3ff
	v_writelane_b32 v249, s3, 53
	s_add_u32 s2, s0, 0x26d90000
	s_addc_u32 s3, s1, 0
	v_writelane_b32 v249, s2, 54
	v_mov_b64_e32 v[160:161], 0x400
	s_mov_b32 s52, 0x8100000
	v_writelane_b32 v249, s3, 55
	s_add_u32 s2, s6, 0x5ca00000
	s_addc_u32 s3, s7, 0
	v_writelane_b32 v249, s2, 56
	s_barrier
	s_nop 0
	v_writelane_b32 v249, s3, 57
	s_add_u32 s2, s0, 0x26c80000
	s_addc_u32 s3, s1, 0
	v_writelane_b32 v249, s2, 58
	s_nop 1
	v_writelane_b32 v249, s3, 59
	s_add_u32 s2, s6, 0x5c600000
	s_addc_u32 s3, s7, 0
	v_writelane_b32 v249, s2, 60
	s_nop 1
	v_writelane_b32 v249, s3, 61
	s_add_u32 s2, s0, 0x24c00000
	s_addc_u32 s3, s1, 0
	v_writelane_b32 v249, s2, 62
	s_nop 1
	v_writelane_b32 v249, s3, 63
	s_add_u32 s2, s6, 0x5c200000
	s_addc_u32 s3, s7, 0
	v_writelane_b32 v250, s2, 0
	s_nop 1
	v_writelane_b32 v250, s3, 1
	s_add_u32 s2, s0, 0x24380000
	s_addc_u32 s3, s1, 0
	v_writelane_b32 v250, s2, 2
	s_nop 1
	v_writelane_b32 v250, s3, 3
	s_add_u32 s2, s6, 0x58200000
	s_addc_u32 s3, s7, 0
	v_writelane_b32 v250, s2, 4
	s_nop 1
	v_writelane_b32 v250, s3, 5
	s_add_u32 s2, s0, 0x26480000
	s_addc_u32 s3, s1, 0
	v_writelane_b32 v250, s2, 6
	s_nop 1
	v_writelane_b32 v250, s3, 7
	s_add_u32 s2, s6, 0x54200000
	s_addc_u32 s3, s7, 0
	v_writelane_b32 v250, s2, 8
	s_nop 1
	v_writelane_b32 v250, s3, 9
	s_add_u32 s2, s0, 0x25c80000
	s_addc_u32 s3, s1, 0
	v_writelane_b32 v250, s2, 10
	s_nop 1
	v_writelane_b32 v250, s3, 11
	s_add_u32 s2, s6, 0x50200000
	s_addc_u32 s3, s7, 0
	v_writelane_b32 v250, s2, 12
	s_nop 1
	v_writelane_b32 v250, s3, 13
	s_add_u32 s2, s0, 0x25480000
	s_addc_u32 s3, s1, 0
	v_writelane_b32 v250, s2, 14
	s_nop 1
	v_writelane_b32 v250, s3, 15
	s_add_u32 s2, s6, 0x30200000
	s_addc_u32 s3, s7, 0
	v_writelane_b32 v250, s2, 16
	s_nop 1
	v_writelane_b32 v250, s3, 17
	s_add_u32 s2, s0, 0x20380000
	s_addc_u32 s3, s1, 0
	v_writelane_b32 v250, s2, 18
	s_nop 1
	v_writelane_b32 v250, s3, 19
	s_add_u32 s2, s6, 0x10200000
	s_addc_u32 s3, s7, 0
	v_writelane_b32 v250, s2, 20
	s_nop 1
	v_writelane_b32 v250, s3, 21
	s_add_u32 s2, s0, 0x1c380000
	s_addc_u32 s3, s1, 0
	v_writelane_b32 v250, s2, 22
	s_nop 1
	v_writelane_b32 v250, s3, 23
	s_add_u32 s2, s0, 0x38334000
	s_addc_u32 s3, s1, 0
	v_writelane_b32 v250, s2, 24
	s_nop 1
	v_writelane_b32 v250, s3, 25
	s_add_u32 s2, s0, 0x38335000
	v_writelane_b32 v250, s2, 26
	s_addc_u32 s2, s1, 0
	v_writelane_b32 v250, s2, 27
	s_add_u32 s2, s0, 0x8100000
	s_addc_u32 s3, s1, 0
	v_writelane_b32 v250, s2, 28
	s_nop 1
	v_writelane_b32 v250, s3, 29
	s_add_u32 s2, s0, 0x10200000
	s_addc_u32 s3, s1, 0
	v_writelane_b32 v250, s2, 30
	s_nop 1
	v_writelane_b32 v250, s3, 31
	s_add_u32 s2, s0, 0x18300000
	s_addc_u32 s3, s1, 0
	v_writelane_b32 v250, s2, 32
	s_nop 1
	v_writelane_b32 v250, s3, 33
	s_add_u32 s2, s0, 0x26fb0000
	s_addc_u32 s3, s1, 0
	v_writelane_b32 v250, s2, 34
	s_nop 1
	v_writelane_b32 v250, s3, 35
	s_add_u32 s2, s0, 0x14280000
	s_addc_u32 s3, s1, 0
	v_writelane_b32 v250, s2, 36
	s_nop 1
	v_writelane_b32 v250, s3, 37
	s_add_u32 s2, s0, 0x8100400
	s_addc_u32 s3, s1, 0
	v_writelane_b32 v250, s2, 38
	s_nop 1
	v_writelane_b32 v250, s3, 39
	s_add_u32 s2, s0, 0x37f34000
	v_writelane_b32 v250, s2, 40
	s_addc_u32 s2, s1, 0
	v_writelane_b32 v250, s2, 41
	s_add_u32 s2, s0, 0x271b4000
	s_addc_u32 s3, s1, 0
	v_writelane_b32 v250, s2, 42
	s_nop 1
	v_writelane_b32 v250, s3, 43
	s_add_u32 s2, s0, 0x2f2b4000
	s_addc_u32 s3, s1, 0
	v_writelane_b32 v250, s2, 44
	s_nop 1
	v_writelane_b32 v250, s3, 45
	s_add_u32 s2, s0, 0x38134000
	v_writelane_b32 v250, s2, 46
	s_addc_u32 s2, s1, 0
	v_writelane_b32 v250, s2, 47
	v_readlane_b32 s2, v249, 6
	s_lshl_b32 s2, s2, 3
	s_add_u32 s3, s0, 0x37f34400
	v_writelane_b32 v250, s3, 48
	s_addc_u32 s3, s1, 0
	s_add_u32 s4, s0, 0x26482000
	v_writelane_b32 v250, s3, 49
	s_addc_u32 s5, s1, 0
	v_writelane_b32 v250, s4, 50
	s_nop 1
	v_writelane_b32 v250, s5, 51
	s_add_u32 s4, s0, 0x25482000
	s_addc_u32 s5, s1, 0
	v_writelane_b32 v250, s4, 52
	s_nop 1
	v_writelane_b32 v250, s5, 53
	s_add_u32 s4, s0, 0x25c80080
	s_addc_u32 s5, s1, 0
	v_writelane_b32 v250, s4, 54
	s_nop 1
	v_writelane_b32 v250, s5, 55
	s_add_u32 s4, s0, 0x26ea2000
	s_addc_u32 s5, s1, 0
	v_writelane_b32 v250, s4, 56
	s_nop 1
	v_writelane_b32 v250, s5, 57
	s_add_u32 s4, s0, 0x26d90080
	s_addc_u32 s5, s1, 0
	v_writelane_b32 v250, s4, 58
	s_add_u32 s0, s0, 0x26c82000
	s_addc_u32 s1, s1, 0
	v_writelane_b32 v250, s5, 59
	v_writelane_b32 v250, s0, 60
	s_mov_b32 s5, 0
	s_mov_b32 s4, s5
	v_writelane_b32 v250, s1, 61
	v_readlane_b32 s0, v249, 7
	s_lshl_b32 s1, s0, 2
	v_writelane_b32 v250, s1, 62
	s_lshl_b32 s0, s0, 6
	v_writelane_b32 v250, s0, 63
	s_add_i32 s0, 0, 0x20000
	v_writelane_b32 v251, s0, 0
	s_add_i32 s0, 0, 0x22000
	v_writelane_b32 v251, s0, 1
	s_add_i32 s0, 0, 0x23400
	v_writelane_b32 v251, s0, 2
	s_add_i32 s0, 0, 0x23440
	v_writelane_b32 v251, s0, 3
	s_mov_b32 s0, s5
	v_writelane_b32 v251, s0, 4
	v_writelane_b32 v251, s2, 5
	s_branch .LBB0_103

; #define PG8_STAGE(bufoff, gbase, voff) do { _Pragma("unroll") for (int _i = 0; _i < 2; ++_i) \
;         __builtin_amdgcn_global_load_lds((const unsigned*)((const char*)(gbase) + (voff)[_i]), (PG8_LAS unsigned*)(lds + (bufoff) + ldsw + _i * 8192), 16, 0, 0); } while (0)
; #define PG8_WAIT_V(n) asm volatile("s_waitcnt vmcnt(" #n ")" ::: "memory")
; #define PG8_BAR __builtin_amdgcn_s_barrier()
;     DI bool next(int i, Unit& u) const {
;     ...
;         int wgid = (int)L; { const int q = nwg / NXCD, r = nwg % NXCD, xcd = wgid % NXCD, off = wgid / NXCD; wgid = (xcd < r ? xcd * (q + 1) : r * (q + 1) + (xcd - r) * q) + off; }
;         const int nig = WGM * nN, gid = wgid / nig, fm = gid * WGM, gsz = (nM - fm) < WGM ? (nM - fm) : WGM;
;         u.pm = fm + ((wgid % nig) % gsz); u.pn = (wgid % nig) / gsz; return true;
; template <class Epi, class Sched>
; __device__ __forceinline__ void gemm_phase(PG8_LAS unsigned char* lds, const Gemm g, const Sched& S, const Epi& E) {
;     ...
;     const char* cA = (const char*)g.A + (size_t)cur.pm * tstep; const char* cB = (const char*)g.Bt + (size_t)cur.pn * tstep;
;     S.a_ready(cur);
;     PG8_STAGE(PG8_SB(0, 0), cB, voffB); PG8_STAGE(PG8_SA(0, 0), cA, voffA); PG8_STAGE(PG8_SB(0, 1), cB + hstep, voffB); PG8_STAGE(PG8_SA(0, 1), cA + hstep, voffA);
;     if (wr == 1) PG8_BAR;
;     PG8_WAIT_V(4); PG8_BAR;
;     PG8_STAGE(PG8_SB(1, 0), cB + kstep, voffB); PG8_STAGE(PG8_SA(1, 0), cA + kstep, voffA); PG8_STAGE(PG8_SB(1, 1), cB + hstep + kstep, voffB);
;     PG8_WAIT_V(6); PG8_BAR;
.LBB0_2727:
	s_or_b64 exec, exec, s[0:1]
	s_mov_b32 s20, 0
	v_writelane_b32 v255, s20, 63
	v_readlane_b32 s20, v249, 6
	v_readlane_b32 s21, v249, 7
	v_mov_b32_e32 v14, v153
.Ltr_m_reenter:
	s_barrier
	s_cmpk_gt_i32 s21, 0x407
	v_readfirstlane_b32 s22, v14
	s_cbranch_scc1 .LBB0_2741
	v_lshlrev_b32_e32 v0, 4, v14
	v_add_u32_e32 v1, 0x2000, v0
	v_ashrrev_i32_e32 v2, 31, v1
	v_lshrrev_b32_e32 v2, 22, v2
	v_add_u32_e32 v2, v1, v2
	v_ashrrev_i32_e32 v8, 10, v2
	v_mul_i32_i24_e32 v3, 0x400, v8
	v_sub_u32_e32 v1, v1, v3
	v_lshrrev_b32_e32 v3, 4, v1
	v_bitop3_b32 v1, v3, v1, 32 bitop3:0x6c
	v_ashrrev_i32_e32 v3, 31, v1
	v_lshrrev_b32_e32 v3, 26, v3
	v_add_u32_e32 v3, v1, v3
	v_ashrrev_i32_e32 v9, 6, v3
	v_and_b32_e32 v3, 0xc0, v3
	v_sub_u32_e32 v1, v1, v3
	v_lshlrev_b32_e32 v2, 5, v8
	v_ashrrev_i16_sdwa v1, v182, sext(v1) dst_sel:DWORD dst_unused:UNUSED_PAD src0_sel:DWORD src1_sel:BYTE_0
	v_and_b32_e32 v2, 32, v2
	v_bfe_i32 v10, v1, 0, 16
	s_ashr_i32 s24, s21, 31
	v_add_u32_e32 v1, v2, v10
	v_lshlrev_b32_e32 v2, 3, v8
	s_lshr_b32 s0, s24, 29
	v_and_b32_e32 v2, 0x1ffff0, v2
	s_add_i32 s0, s21, s0
	s_ashr_i32 s1, s22, 6
	v_add_lshl_u32 v2, v9, v2, 11
	s_ashr_i32 s3, s0, 3
	s_and_b32 s0, s0, -8
	s_ashr_i32 s2, s22, 8
	s_lshl_b32 s23, s1, 10
	v_lshl_add_u32 v134, v1, 1, v2
	v_bfe_i32 v2, v14, 27, 1
	s_sub_i32 s0, s21, s0
	v_lshrrev_b32_e32 v2, 22, v2
	s_cmp_lt_i32 s0, 0
	s_movk_i32 s4, 0x82
	v_add_u32_e32 v2, v0, v2
	s_cselect_b32 s4, s4, 0x81
	v_and_b32_e32 v2, 0xfffffc00, v2
	s_mul_i32 s0, s4, s0
	v_sub_u32_e32 v0, v0, v2
	s_add_i32 s0, s0, s3
	v_lshrrev_b32_e32 v2, 4, v0
	s_ashr_i32 s3, s0, 31
	v_bitop3_b32 v2, v2, v0, 32 bitop3:0x6c
	v_ashrrev_i32_e32 v0, 31, v0
	s_lshr_b32 s3, s3, 27
	v_lshrrev_b32_e32 v0, 26, v0
	s_add_i32 s3, s0, s3
	v_ashrrev_i32_e32 v1, 31, v14
	v_add_u32_e32 v0, v2, v0
	s_ashr_i32 s4, s3, 5
	v_lshrrev_b32_e32 v1, 26, v1
	v_ashrrev_i32_e32 v12, 6, v0
	s_lshl_b32 s6, s4, 3
	v_add_u32_e32 v1, v14, v1
	v_mul_i32_i24_e32 v0, 64, v12
	s_sub_i32 s4, 0x102, s6
	v_ashrrev_i32_e32 v11, 6, v1
	v_sub_u32_e32 v0, v2, v0
	s_min_u32 s7, s4, 8
	s_andn2_b32 s3, s3, 31
	v_lshlrev_b32_e32 v1, 5, v11
	v_ashrrev_i16_sdwa v0, v182, sext(v0) dst_sel:DWORD dst_unused:UNUSED_PAD src0_sel:DWORD src1_sel:BYTE_0
	s_sub_i32 s3, s0, s3
	v_cvt_f32_ubyte0_e32 v3, s7
	v_and_b32_e32 v1, 32, v1
	v_bfe_i32 v13, v0, 0, 16
	v_cvt_f32_i32_e32 v2, s3
	v_rcp_iflag_f32_e32 v4, v3
	v_add_u32_e32 v0, v1, v13
	v_lshlrev_b32_e32 v1, 3, v11
	v_and_b32_e32 v1, 0x1ffff0, v1
	v_add_lshl_u32 v1, v12, v1, 11
	v_lshl_add_u32 v136, v0, 1, v1
	v_mul_f32_e32 v0, v2, v4
	v_trunc_f32_e32 v0, v0
	v_fma_f32 v1, -v0, v3, v2
	v_cvt_i32_f32_e32 v0, v0
	s_ashr_i32 s0, s3, 30
	s_or_b32 s0, s0, 1
	v_cmp_ge_f32_e64 s[4:5], |v1|, v3
	s_and_b64 s[4:5], s[4:5], exec
	s_cselect_b32 s0, s0, 0
	v_readfirstlane_b32 s4, v0
	s_add_i32 s0, s4, s0
	s_mul_i32 s4, s0, s7
	s_sub_i32 s3, s3, s4
	s_sext_i32_i8 s3, s3
	s_add_i32 s10, s6, s3
	s_cmpk_lt_u32 s21, 0x400
	s_cbranch_scc0 .Ltr_m_left
	s_and_b32 s0, s21, 7
	s_lshl_b32 s0, s0, 7
	s_lshr_b32 s3, s21, 3
	s_or_b32 s0, s0, s3
	s_lshr_b32 s10, s0, 5
	s_lshl_b32 s10, s10, 3
	s_and_b32 s3, s0, 7
	s_or_b32 s10, s10, s3
	s_bfe_u32 s0, s0, 0x20003
	s_branch .Ltr_m_join
.Ltr_m_left:
	s_and_b32 s0, s21, 7
	s_and_b32 s3, s0, 1
	s_add_i32 s10, s3, 0x100
	s_lshr_b32 s0, s0, 1
.Ltr_m_join:
	s_ashr_i32 s11, s10, 31
	s_bfe_i64 s[6:7], s[0:1], 0x80000
	s_lshl_b64 s[4:5], s[10:11], 19
	s_lshl_b64 s[6:7], s[6:7], 19
	v_readlane_b32 s3, v250, 40
	s_add_u32 s14, s3, s6
	v_readlane_b32 s3, v250, 41
	s_addc_u32 s15, s3, s7
	s_add_i32 s25, s23, 0
	s_add_i32 m0, s25, 0x10000
	v_readlane_b32 s6, v250, 28
	global_load_lds_dwordx4 v136, s[14:15]
	s_add_i32 m0, s25, 0x12000
	v_readlane_b32 s7, v250, 29
	s_add_u32 s12, s6, s4
	global_load_lds_dwordx4 v134, s[14:15]
	s_addc_u32 s13, s7, s5
	s_mov_b32 m0, s25
	s_add_i32 s26, s25, 0x2000
	global_load_lds_dwordx4 v136, s[12:13]
	s_mov_b32 m0, s26
	s_add_u32 s4, s14, 0x40000
	global_load_lds_dwordx4 v134, s[12:13]
	s_addc_u32 s5, s15, 0
	s_add_i32 m0, s25, 0x14000
	v_mov_b32_e32 v137, v17
	global_load_lds_dwordx4 v136, s[4:5]
	s_add_i32 m0, s25, 0x16000
	v_mov_b32_e32 v135, v17
	global_load_lds_dwordx4 v134, s[4:5]
	s_add_u32 s4, s12, 0x40000
	s_addc_u32 s5, s13, 0
	s_add_i32 s27, s25, 0x4000
	s_mov_b32 m0, s27
	s_add_i32 s28, s25, 0x6000
	global_load_lds_dwordx4 v136, s[4:5]
	s_mov_b32 m0, s28
	v_lshl_add_u64 v[6:7], s[14:15], 0, v[136:137]
	global_load_lds_dwordx4 v134, s[4:5]
	v_lshl_add_u64 v[4:5], s[14:15], 0, v[134:135]
	v_lshl_add_u64 v[2:3], s[12:13], 0, v[136:137]
	s_cmp_lg_u32 s2, 1
	v_lshl_add_u64 v[0:1], s[12:13], 0, v[134:135]
	s_cbranch_scc1 .LBB0_2730
	s_barrier

;     DI bool next(int i, Unit& u) const {
;         const long L = (long)i * G + c; if (L >= nwg) return false;
;         int wgid = (int)L; { const int q = nwg / NXCD, r = nwg % NXCD, xcd = wgid % NXCD, off = wgid / NXCD; wgid = (xcd < r ? xcd * (q + 1) : r * (q + 1) + (xcd - r) * q) + off; }
;         const int nig = WGM * nN, gid = wgid / nig, fm = gid * WGM, gsz = (nM - fm) < WGM ? (nM - fm) : WGM;
;         u.pm = fm + ((wgid % nig) % gsz); u.pn = (wgid % nig) / gsz; return true;
; template <class Epi, class Sched>
; __device__ __forceinline__ void gemm_phase(PG8_LAS unsigned char* lds, const Gemm g, const Sched& S, const Epi& E) {
;     ...
;         const bool has_next = S.next(ui + 1, nxt);
;         const char* nA = has_next ? (const char*)g.A + (size_t)nxt.pm * tstep : cA; const char* nB = has_next ? (const char*)g.Bt + (size_t)nxt.pn * tstep : cB;
.LBB0_2732:
	s_add_i32 s35, s35, 1
	s_mul_i32 s0, s35, s34
	s_mul_hi_u32 s1, s35, s20
	s_add_i32 s1, s1, s0
	s_mul_i32 s0, s35, s20
	s_add_u32 s6, s0, s21
	s_addc_u32 s7, s1, s24
	v_cmp_gt_i64_e64 s[0:1], s[6:7], v[158:159]
	s_and_b64 vcc, exec, s[0:1]
	s_cbranch_vccnz .LBB0_2734
	s_and_b32 s2, s6, 7
	s_lshl_b32 s2, s2, 7
	s_lshr_b32 s3, s6, 3
	s_or_b32 s2, s2, s3
	s_lshr_b32 s4, s2, 5
	s_lshl_b32 s4, s4, 3
	s_and_b32 s3, s2, 7
	s_or_b32 s4, s4, s3
	s_bfe_u32 s2, s2, 0x20003

; DI int otid() { int t = threadIdx.x; asm volatile("" : "+v"(t)); return t; }
; DI void gbar(unsigned* ctr, unsigned target) {
;   asm volatile("s_waitcnt vmcnt(0)" ::: "memory");
;   __syncthreads();
;   if (otid() == 0) {
;     __builtin_amdgcn_fence(__ATOMIC_RELEASE, "agent");
;     asm volatile("s_waitcnt vmcnt(0)" ::: "memory");
;     __hip_atomic_fetch_add(ctr, 1u, __ATOMIC_RELAXED, __HIP_MEMORY_SCOPE_AGENT);
;     while (__hip_atomic_load(ctr, __ATOMIC_RELAXED, __HIP_MEMORY_SCOPE_AGENT) < target) __builtin_amdgcn_s_sleep(2);
;     __builtin_amdgcn_fence(__ATOMIC_ACQUIRE, "agent");
;     asm volatile("s_waitcnt vmcnt(0)" ::: "memory");
;   }
;   __syncthreads();
; }
.LBB0_2741:
	s_waitcnt vmcnt(0)
	s_waitcnt lgkmcnt(0)
	s_barrier
	v_readlane_b32 s6, v255, 63
	v_readlane_b32 s7, v249, 7
	v_cmp_eq_u32_e32 vcc, 0, v153
	s_and_saveexec_b64 s[0:1], vcc
	s_cbranch_execz .Ltr_m_arr
	buffer_wbl2 sc1
	s_waitcnt vmcnt(0)
	v_readlane_b32 s2, v249, 44
	v_readlane_b32 s3, v249, 45
	s_lshl_b32 s4, s6, 2
	s_add_u32 s2, s2, s4
	s_addc_u32 s3, s3, 0
	s_nop 4
	global_atomic_add v17, v182, s[2:3]
.Ltr_m_arr:
	s_or_b64 exec, exec, s[0:1]
	s_cmp_lg_u32 s6, 0
	s_cbranch_scc1 .Ltr_m_wait
	s_cmp_lt_u32 s7, 8
	s_cbranch_scc0 .Ltr_m_wait
	s_mov_b32 s2, 1
	v_writelane_b32 v255, s2, 63
	v_readlane_b32 s20, v249, 6
	s_add_i32 s21, s7, 0x400
	v_mov_b32_e32 v14, v153
	s_branch .Ltr_m_reenter
.Ltr_m_wait:
	v_cmp_eq_u32_e32 vcc, 0, v153
	s_and_saveexec_b64 s[0:1], vcc
	s_cbranch_execz .LBB0_2747
	v_readlane_b32 s4, v249, 44
	v_readlane_b32 s5, v249, 45
	v_readlane_b32 s2, v251, 4
	s_add_i32 s2, s2, 3
	v_readlane_b32 s3, v249, 6
	s_mul_i32 s2, s2, s3
	s_nop 1
	global_load_dword v0, v17, s[4:5] sc1
	s_waitcnt vmcnt(0)
	v_cmp_le_u32_e32 vcc, s2, v0
	s_cbranch_vccnz .LBB0_2746

; #define PG8_STAGE(bufoff, gbase, voff) do { _Pragma("unroll") for (int _i = 0; _i < 2; ++_i) \
;         __builtin_amdgcn_global_load_lds((const unsigned*)((const char*)(gbase) + (voff)[_i]), (PG8_LAS unsigned*)(lds + (bufoff) + ldsw + _i * 8192), 16, 0, 0); } while (0)
; #define PG8_WAIT_V(n) asm volatile("s_waitcnt vmcnt(" #n ")" ::: "memory")
; #define PG8_BAR __builtin_amdgcn_s_barrier()
;     DI bool next(int i, Unit& u) const {
;     ...
;         int wgid = (int)L; { const int q = nwg / NXCD, r = nwg % NXCD, xcd = wgid % NXCD, off = wgid / NXCD; wgid = (xcd < r ? xcd * (q + 1) : r * (q + 1) + (xcd - r) * q) + off; }
;         const int nig = WGM * nN, gid = wgid / nig, fm = gid * WGM, gsz = (nM - fm) < WGM ? (nM - fm) : WGM;
;         u.pm = fm + ((wgid % nig) % gsz); u.pn = (wgid % nig) / gsz; return true;
; template <class Epi, class Sched>
; __device__ __forceinline__ void gemm_phase(PG8_LAS unsigned char* lds, const Gemm g, const Sched& S, const Epi& E) {
;     ...
;     const char* cA = (const char*)g.A + (size_t)cur.pm * tstep; const char* cB = (const char*)g.Bt + (size_t)cur.pn * tstep;
;     S.a_ready(cur);
;     PG8_STAGE(PG8_SB(0, 0), cB, voffB); PG8_STAGE(PG8_SA(0, 0), cA, voffA); PG8_STAGE(PG8_SB(0, 1), cB + hstep, voffB); PG8_STAGE(PG8_SA(0, 1), cA + hstep, voffA);
;     if (wr == 1) PG8_BAR;
;     PG8_WAIT_V(4); PG8_BAR;
;     PG8_STAGE(PG8_SB(1, 0), cB + kstep, voffB); PG8_STAGE(PG8_SA(1, 0), cA + kstep, voffA); PG8_STAGE(PG8_SB(1, 1), cB + hstep + kstep, voffB);
;     PG8_WAIT_V(6); PG8_BAR;
.LBB0_2747:
	s_or_b64 exec, exec, s[0:1]
	s_mov_b32 s18, 0
	v_writelane_b32 v255, s18, 63
	v_readlane_b32 s18, v249, 6
	v_readlane_b32 s19, v249, 7
	v_mov_b32_e32 v14, v153
.Ltr_o_reenter:
	s_barrier
	s_cmpk_gt_i32 s19, 0x407
	v_readfirstlane_b32 s20, v14
	s_cbranch_scc1 .LBB0_2759
	v_lshlrev_b32_e32 v0, 4, v14
	v_add_u32_e32 v1, 0x2000, v0
	v_ashrrev_i32_e32 v2, 31, v1
	v_lshrrev_b32_e32 v2, 22, v2
	v_add_u32_e32 v2, v1, v2
	v_ashrrev_i32_e32 v8, 10, v2
	v_mul_i32_i24_e32 v3, 0x400, v8
	v_sub_u32_e32 v1, v1, v3
	v_lshrrev_b32_e32 v3, 4, v1
	v_bitop3_b32 v1, v3, v1, 32 bitop3:0x6c
	v_ashrrev_i32_e32 v3, 31, v1
	v_lshrrev_b32_e32 v3, 26, v3
	v_add_u32_e32 v3, v1, v3
	v_ashrrev_i32_e32 v9, 6, v3
	v_and_b32_e32 v3, 0xc0, v3
	v_sub_u32_e32 v1, v1, v3
	v_lshlrev_b32_e32 v2, 5, v8
	v_ashrrev_i16_sdwa v1, v182, sext(v1) dst_sel:DWORD dst_unused:UNUSED_PAD src0_sel:DWORD src1_sel:BYTE_0
	v_and_b32_e32 v2, 32, v2
	v_bfe_i32 v10, v1, 0, 16
	s_ashr_i32 s22, s19, 31
	v_add_u32_e32 v1, v2, v10
	v_lshlrev_b32_e32 v2, 3, v8
	s_lshr_b32 s0, s22, 29
	v_and_b32_e32 v2, 0x1ffff0, v2
	s_add_i32 s0, s19, s0
	s_ashr_i32 s1, s20, 6
	v_add_lshl_u32 v2, v9, v2, 11
	s_ashr_i32 s3, s0, 3
	s_and_b32 s0, s0, -8
	s_ashr_i32 s2, s20, 8
	s_lshl_b32 s21, s1, 10
	v_lshl_add_u32 v18, v1, 1, v2
	v_bfe_i32 v2, v14, 27, 1
	s_sub_i32 s0, s19, s0
	v_lshrrev_b32_e32 v2, 22, v2
	s_cmp_lt_i32 s0, 0
	s_movk_i32 s4, 0x82
	v_add_u32_e32 v2, v0, v2
	s_cselect_b32 s4, s4, 0x81
	v_and_b32_e32 v2, 0xfffffc00, v2
	s_mul_i32 s0, s4, s0
	v_sub_u32_e32 v0, v0, v2
	s_add_i32 s0, s0, s3
	v_lshrrev_b32_e32 v2, 4, v0
	s_ashr_i32 s3, s0, 31
	v_bitop3_b32 v2, v2, v0, 32 bitop3:0x6c
	v_ashrrev_i32_e32 v0, 31, v0
	s_lshr_b32 s3, s3, 27
	v_lshrrev_b32_e32 v0, 26, v0
	s_add_i32 s3, s0, s3
	v_ashrrev_i32_e32 v1, 31, v14
	v_add_u32_e32 v0, v2, v0
	s_ashr_i32 s4, s3, 5
	v_lshrrev_b32_e32 v1, 26, v1
	v_ashrrev_i32_e32 v12, 6, v0
	s_lshl_b32 s6, s4, 3
	v_add_u32_e32 v1, v14, v1
	v_mul_i32_i24_e32 v0, 64, v12
	s_sub_i32 s4, 0x102, s6
	v_ashrrev_i32_e32 v11, 6, v1
	v_sub_u32_e32 v0, v2, v0
	s_min_u32 s7, s4, 8
	s_andn2_b32 s3, s3, 31
	v_lshlrev_b32_e32 v1, 5, v11
	v_ashrrev_i16_sdwa v0, v182, sext(v0) dst_sel:DWORD dst_unused:UNUSED_PAD src0_sel:DWORD src1_sel:BYTE_0
	s_sub_i32 s3, s0, s3
	v_cvt_f32_ubyte0_e32 v3, s7
	v_and_b32_e32 v1, 32, v1
	v_bfe_i32 v13, v0, 0, 16
	v_cvt_f32_i32_e32 v2, s3
	v_rcp_iflag_f32_e32 v4, v3
	v_add_u32_e32 v0, v1, v13
	v_lshlrev_b32_e32 v1, 3, v11
	v_and_b32_e32 v1, 0x1ffff0, v1
	v_add_lshl_u32 v1, v12, v1, 11
	v_lshl_add_u32 v134, v0, 1, v1
	v_mul_f32_e32 v0, v2, v4
	v_trunc_f32_e32 v0, v0
	v_fma_f32 v1, -v0, v3, v2
	v_cvt_i32_f32_e32 v0, v0
	s_ashr_i32 s0, s3, 30
	s_or_b32 s0, s0, 1
	v_cmp_ge_f32_e64 s[4:5], |v1|, v3
	s_and_b64 s[4:5], s[4:5], exec
	s_cselect_b32 s0, s0, 0
	v_readfirstlane_b32 s4, v0
	s_add_i32 s0, s4, s0
	s_mul_i32 s4, s0, s7
	s_sub_i32 s3, s3, s4
	s_sext_i32_i8 s3, s3
	s_add_i32 s10, s6, s3
	s_cmpk_lt_u32 s19, 0x400
	s_cbranch_scc0 .Ltr_o_left
	s_and_b32 s0, s19, 7
	s_lshl_b32 s0, s0, 7
	s_lshr_b32 s3, s19, 3
	s_or_b32 s0, s0, s3
	s_lshr_b32 s10, s0, 5
	s_lshl_b32 s10, s10, 3
	s_and_b32 s3, s0, 7
	s_or_b32 s10, s10, s3
	s_bfe_u32 s0, s0, 0x20003
	s_branch .Ltr_o_join
.Ltr_o_left:
	s_and_b32 s0, s19, 7
	s_and_b32 s3, s0, 1
	s_add_i32 s10, s3, 0x100
	s_lshr_b32 s0, s0, 1
.Ltr_o_join:
	s_ashr_i32 s11, s10, 31
	s_bfe_i64 s[6:7], s[0:1], 0x80000
	s_lshl_b64 s[4:5], s[10:11], 19
	s_lshl_b64 s[6:7], s[6:7], 19
	v_readlane_b32 s3, v250, 46
	s_add_u32 s14, s3, s6
	v_readlane_b32 s3, v250, 47
	s_addc_u32 s15, s3, s7
	s_add_i32 s23, s21, 0
	s_add_i32 m0, s23, 0x10000
	v_readlane_b32 s6, v250, 30
	global_load_lds_dwordx4 v134, s[14:15]
	s_add_i32 m0, s23, 0x12000
	v_readlane_b32 s7, v250, 31
	s_add_u32 s12, s6, s4
	global_load_lds_dwordx4 v18, s[14:15]
	s_addc_u32 s13, s7, s5
	s_mov_b32 m0, s23
	s_add_i32 s24, s23, 0x2000
	global_load_lds_dwordx4 v134, s[12:13]
	s_mov_b32 m0, s24
	s_add_u32 s4, s14, 0x40000
	global_load_lds_dwordx4 v18, s[12:13]
	s_addc_u32 s5, s15, 0
	s_add_i32 m0, s23, 0x14000
	v_mov_b32_e32 v135, v17
	global_load_lds_dwordx4 v134, s[4:5]
	s_add_i32 m0, s23, 0x16000
	v_mov_b32_e32 v19, v17
	global_load_lds_dwordx4 v18, s[4:5]
	s_add_u32 s4, s12, 0x40000
	s_addc_u32 s5, s13, 0
	s_add_i32 s25, s23, 0x4000
	s_mov_b32 m0, s25
	s_add_i32 s26, s23, 0x6000
	global_load_lds_dwordx4 v134, s[4:5]
	s_mov_b32 m0, s26
	v_lshl_add_u64 v[6:7], s[14:15], 0, v[134:135]
	global_load_lds_dwordx4 v18, s[4:5]
	v_lshl_add_u64 v[4:5], s[14:15], 0, v[18:19]
	v_lshl_add_u64 v[2:3], s[12:13], 0, v[134:135]
	s_cmp_lg_u32 s2, 1
	v_lshl_add_u64 v[0:1], s[12:13], 0, v[18:19]
	s_cbranch_scc1 .LBB0_2750
	s_barrier

;     DI bool next(int i, Unit& u) const {
;         const long L = (long)i * G + c; if (L >= nwg) return false;
;         int wgid = (int)L; { const int q = nwg / NXCD, r = nwg % NXCD, xcd = wgid % NXCD, off = wgid / NXCD; wgid = (xcd < r ? xcd * (q + 1) : r * (q + 1) + (xcd - r) * q) + off; }
;         const int nig = WGM * nN, gid = wgid / nig, fm = gid * WGM, gsz = (nM - fm) < WGM ? (nM - fm) : WGM;
;         u.pm = fm + ((wgid % nig) % gsz); u.pn = (wgid % nig) / gsz; return true;
; template <class Epi, class Sched>
; __device__ __forceinline__ void gemm_phase(PG8_LAS unsigned char* lds, const Gemm g, const Sched& S, const Epi& E) {
;     ...
;         const bool has_next = S.next(ui + 1, nxt);
;         const char* nA = has_next ? (const char*)g.A + (size_t)nxt.pm * tstep : cA; const char* nB = has_next ? (const char*)g.Bt + (size_t)nxt.pn * tstep : cB;
.LBB0_2751:
	s_add_i32 s30, s30, 1
	s_mul_i32 s0, s30, s29
	s_mul_hi_u32 s1, s30, s18
	s_add_i32 s1, s1, s0
	s_mul_i32 s0, s30, s18
	s_add_u32 s6, s0, s19
	s_addc_u32 s7, s1, s22
	v_cmp_gt_i64_e64 s[0:1], s[6:7], v[158:159]
	s_and_b64 vcc, exec, s[0:1]
	s_cbranch_vccnz .LBB0_2753
	s_and_b32 s2, s6, 7
	s_lshl_b32 s2, s2, 7
	s_lshr_b32 s3, s6, 3
	s_or_b32 s2, s2, s3
	s_lshr_b32 s4, s2, 5
	s_lshl_b32 s4, s4, 3
	s_and_b32 s3, s2, 7
	s_or_b32 s4, s4, s3
	s_bfe_u32 s2, s2, 0x20003

; DI int otid() { int t = threadIdx.x; asm volatile("" : "+v"(t)); return t; }
; DI void gbar(unsigned* ctr, unsigned target) {
;   asm volatile("s_waitcnt vmcnt(0)" ::: "memory");
;   __syncthreads();
;   if (otid() == 0) {
;     __builtin_amdgcn_fence(__ATOMIC_RELEASE, "agent");
;     asm volatile("s_waitcnt vmcnt(0)" ::: "memory");
;     __hip_atomic_fetch_add(ctr, 1u, __ATOMIC_RELAXED, __HIP_MEMORY_SCOPE_AGENT);
;     while (__hip_atomic_load(ctr, __ATOMIC_RELAXED, __HIP_MEMORY_SCOPE_AGENT) < target) __builtin_amdgcn_s_sleep(2);
;     __builtin_amdgcn_fence(__ATOMIC_ACQUIRE, "agent");
;     asm volatile("s_waitcnt vmcnt(0)" ::: "memory");
;   }
;   __syncthreads();
; }
; __global__ void __launch_bounds__(512, 2) mega_kernel(Params p) {
;     ...
;     gbar(bar, ++nb * G);
;     phase_out(p, smem);
;     gbar(bar, ++nb * G);
.LBB0_2759:
	s_waitcnt vmcnt(0)
	v_readlane_b32 s2, v255, 63
	v_readlane_b32 s3, v249, 7
	s_cmp_lg_u32 s2, 0
	s_cbranch_scc1 .Ltr_o_done
	s_sub_u32 s3, s3, 8
	s_cmp_lt_u32 s3, 8
	s_cbranch_scc0 .Ltr_o_done
	s_waitcnt lgkmcnt(0)
	v_cmp_eq_u32_e32 vcc, 0, v153
	s_and_saveexec_b64 s[0:1], vcc
	s_cbranch_execz .Ltr_o_go
	v_readlane_b32 s4, v249, 44
	v_readlane_b32 s5, v249, 45
	v_readlane_b32 s2, v251, 8
	s_lshl_b32 s2, s2, 3
	s_add_i32 s2, s2, 8
	s_nop 3
	global_load_dword v0, v17, s[4:5] offset:4 sc1
	s_waitcnt vmcnt(0)
	v_cmp_le_u32_e32 vcc, s2, v0
	s_cbranch_vccnz .Ltr_o_spun
.Ltr_o_spin:
	s_sleep 2
	global_load_dword v0, v17, s[4:5] offset:4 sc1
	s_waitcnt vmcnt(0)
	v_cmp_gt_u32_e32 vcc, s2, v0
	s_cbranch_vccnz .Ltr_o_spin

; DI int otid() { int t = threadIdx.x; asm volatile("" : "+v"(t)); return t; }
; DI void gbar(unsigned* ctr, unsigned target) {
;   asm volatile("s_waitcnt vmcnt(0)" ::: "memory");
;   __syncthreads();
;   if (otid() == 0) {
;     __builtin_amdgcn_fence(__ATOMIC_RELEASE, "agent");
;     asm volatile("s_waitcnt vmcnt(0)" ::: "memory");
;     __hip_atomic_fetch_add(ctr, 1u, __ATOMIC_RELAXED, __HIP_MEMORY_SCOPE_AGENT);
;     while (__hip_atomic_load(ctr, __ATOMIC_RELAXED, __HIP_MEMORY_SCOPE_AGENT) < target) __builtin_amdgcn_s_sleep(2);
;     __builtin_amdgcn_fence(__ATOMIC_ACQUIRE, "agent");
;     asm volatile("s_waitcnt vmcnt(0)" ::: "memory");
;   }
;   __syncthreads();
; }
.Ltr_o_go:
	s_or_b64 exec, exec, s[0:1]
	s_mov_b32 s2, 1
	v_writelane_b32 v255, s2, 63
	v_readlane_b32 s18, v249, 6
	s_add_i32 s19, s3, 0x400
	v_mov_b32_e32 v14, v153
	s_branch .Ltr_o_reenter
.Ltr_o_done:
	v_readlane_b32 s0, v251, 4
	v_mov_b32_e32 v0, v153
	s_add_i32 s18, s0, 4
	s_waitcnt lgkmcnt(0)
	s_barrier
	s_nop 0
	v_cmp_eq_u32_e32 vcc, 0, v0
	s_and_saveexec_b64 s[0:1], vcc
	s_cbranch_execz .LBB0_2765
	s_mov_b64 s[2:3], exec
	buffer_wbl2 sc1
	s_waitcnt vmcnt(0)
	s_waitcnt vmcnt(0)
	v_mbcnt_lo_u32_b32 v0, s2, 0
	v_mbcnt_hi_u32_b32 v0, s3, v0
	v_cmp_eq_u32_e32 vcc, 0, v0
	s_and_saveexec_b64 s[4:5], vcc
	s_cbranch_execz .LBB0_2762
	s_bcnt1_i32_b64 s2, s[2:3]
	v_mov_b32_e32 v0, s2
	v_readlane_b32 s2, v249, 44
	v_readlane_b32 s3, v249, 45
	s_nop 4
	global_atomic_add v17, v0, s[2:3]
